# up-projection conv epilogue: dropped the zero-fill of 32 shifted-operand registers in the first row block (only feeds the two rows the fix-up pass overwrites)
# baseline (speedup 1.0000x reference)
; __device__ __forceinline__ unsigned pk2(float lo, float hi) { const f32x2 v = {lo, hi}; return __builtin_bit_cast(unsigned, __builtin_convertvector(v, bf16x2_t)); }
; __device__ __forceinline__ float silu(float x) { return x * __builtin_amdgcn_rcpf(1.f + __builtin_amdgcn_exp2f(-1.4426950408889634f * x)); }
; __device__ __forceinline__ float dpp_prev(float cur, float prevblk, int which) {
;     const int c = __float_as_int(cur), p = __float_as_int(prevblk);
;     if (which == 1) { const int t = __builtin_amdgcn_mov_dpp(p, 0x121, 0xf, 0xf, true); return __int_as_float(__builtin_amdgcn_update_dpp(t, c, 0x111, 0xf, 0xf, false)); }
;     const int t = __builtin_amdgcn_mov_dpp(p, 0x122, 0xf, 0xf, true); return __int_as_float(__builtin_amdgcn_update_dpp(t, c, 0x112, 0xf, 0xf, false));
; }
;     __device__ __forceinline__ void operator()(f32x4 (&acc)[2][2][4][2], const Unit& u, int, int, int, int) const {
;     ...
; #pragma unroll
;         for (int ai = 0; ai < 2; ++ai)
; #pragma unroll
;             for (int m = 0; m < 4; ++m) { float r[8];
; #pragma unroll
;                 for (int n = 0; n < 2; ++n)
; #pragma unroll
;                     for (int e = 0; e < 4; ++e) { const float A = acc[ai][0][m][n][e], Gv = acc[ai][1][m][n][e];
;                         const float Ap = m > 0 ? acc[ai][0][m > 0 ? m - 1 : 0][n][e] : 0.f, Gp = m > 0 ? acc[ai][1][m > 0 ? m - 1 : 0][n][e] : 0.f;
;                         const float a1 = dpp_prev(A, Ap, 1), a2 = dpp_prev(A, Ap, 2), g1 = dpp_prev(Gv, Gp, 1), g2 = dpp_prev(Gv, Gp, 2);
;                         const float ca = ba[n][e] + wa0[n][e] * a2 + wa1[n][e] * a1 + wa2[n][e] * A, cg = bg[n][e] + wg0[n][e] * g2 + wg1[n][e] * g1 + wg2[n][e] * Gv;
;                         r[4 * n + e] = silu(ca) * cg; }
;                 if (!(m == 0 && fr < 2)) { u32x4 w; w.x = pk2(r[0], r[1]); w.y = pk2(r[2], r[3]); w.z = pk2(r[4], r[5]); w.w = pk2(r[6], r[7]);
;                     *(u32x4*)(ACT + (size_t)(rowt + ai * HALF + m * 16) * NFF + f0) = w; }
;                 __builtin_amdgcn_sched_barrier(0); }
.LBB0_1466:
	s_or_b64 exec, exec, s[12:13]
	v_mov_b32_dpp v218, v188 row_shr:1 row_mask:0xf bank_mask:0xf
	v_mov_b32_dpp v220, v188 row_shr:2 row_mask:0xf bank_mask:0xf
	v_mov_b32_dpp v214, v184 row_shr:1 row_mask:0xf bank_mask:0xf
	v_mov_b32_dpp v216, v184 row_shr:2 row_mask:0xf bank_mask:0xf
	v_mov_b32_dpp v219, v189 row_shr:1 row_mask:0xf bank_mask:0xf
	v_mov_b32_dpp v221, v189 row_shr:2 row_mask:0xf bank_mask:0xf
	v_mov_b32_dpp v215, v185 row_shr:1 row_mask:0xf bank_mask:0xf
	v_mov_b32_dpp v217, v185 row_shr:2 row_mask:0xf bank_mask:0xf
	v_mov_b32_dpp v230, v190 row_shr:1 row_mask:0xf bank_mask:0xf
	v_mov_b32_dpp v232, v190 row_shr:2 row_mask:0xf bank_mask:0xf
	v_mov_b32_dpp v226, v186 row_shr:1 row_mask:0xf bank_mask:0xf
	v_mov_b32_dpp v228, v186 row_shr:2 row_mask:0xf bank_mask:0xf
	v_mov_b32_dpp v231, v191 row_shr:1 row_mask:0xf bank_mask:0xf
	v_mov_b32_dpp v233, v191 row_shr:2 row_mask:0xf bank_mask:0xf
	v_mov_b32_dpp v227, v187 row_shr:1 row_mask:0xf bank_mask:0xf
	v_mov_b32_dpp v229, v187 row_shr:2 row_mask:0xf bank_mask:0xf
	v_mov_b32_dpp v238, v180 row_shr:1 row_mask:0xf bank_mask:0xf
	v_mov_b32_dpp v240, v180 row_shr:2 row_mask:0xf bank_mask:0xf
	v_mov_b32_dpp v234, v176 row_shr:1 row_mask:0xf bank_mask:0xf
	v_mov_b32_dpp v236, v176 row_shr:2 row_mask:0xf bank_mask:0xf
	v_mov_b32_dpp v239, v181 row_shr:1 row_mask:0xf bank_mask:0xf
	v_mov_b32_dpp v241, v181 row_shr:2 row_mask:0xf bank_mask:0xf
	v_mov_b32_dpp v235, v177 row_shr:1 row_mask:0xf bank_mask:0xf
	v_mov_b32_dpp v237, v177 row_shr:2 row_mask:0xf bank_mask:0xf
	v_mov_b32_dpp v222, v182 row_shr:1 row_mask:0xf bank_mask:0xf
	v_mov_b32_dpp v224, v182 row_shr:2 row_mask:0xf bank_mask:0xf
	v_mov_b32_dpp v210, v178 row_shr:1 row_mask:0xf bank_mask:0xf
	v_mov_b32_dpp v212, v178 row_shr:2 row_mask:0xf bank_mask:0xf
	v_mov_b32_dpp v223, v183 row_shr:1 row_mask:0xf bank_mask:0xf
	v_mov_b32_dpp v225, v183 row_shr:2 row_mask:0xf bank_mask:0xf
	v_mov_b32_dpp v211, v179 row_shr:1 row_mask:0xf bank_mask:0xf
	v_mov_b32_dpp v213, v179 row_shr:2 row_mask:0xf bank_mask:0xf
	s_waitcnt vmcnt(8) lgkmcnt(0)
	s_and_saveexec_b64 s[8:9], s[6:7]
	s_xor_b64 s[8:9], exec, s[8:9]
	s_cbranch_execz .LBB0_1468
	v_pk_fma_f32 v[240:241], v[100:101], v[240:241], v[112:113]
	v_pk_fma_f32 v[232:233], v[154:155], v[232:233], v[158:159]
	v_pk_fma_f32 v[238:239], v[108:109], v[238:239], v[240:241]
	v_pk_fma_f32 v[230:231], v[150:151], v[230:231], v[232:233]
	v_pk_fma_f32 v[238:239], v[180:181], v[104:105], v[238:239]
	v_pk_fma_f32 v[230:231], v[190:191], v[146:147], v[230:231]
	v_mul_f32_e32 v240, 0xbfb8aa3b, v238
	v_mul_f32_e32 v241, 0xbfb8aa3b, v239
	v_exp_f32_e32 v240, v240
	v_exp_f32_e32 v241, v241
	v_pk_fma_f32 v[236:237], v[84:85], v[236:237], v[96:97]
	v_mul_f32_e32 v232, 0xbfb8aa3b, v230
	v_add_f32_e32 v240, 1.0, v240
	v_add_f32_e32 v241, 1.0, v241
	v_rcp_f32_e32 v240, v240
	v_rcp_f32_e32 v241, v241
	v_pk_fma_f32 v[234:235], v[88:89], v[234:235], v[236:237]
	v_pk_fma_f32 v[220:221], v[152:153], v[220:221], v[156:157]
	v_pk_fma_f32 v[234:235], v[176:177], v[92:93], v[234:235]
	v_pk_mul_f32 v[236:237], v[238:239], v[240:241]
	v_exp_f32_e32 v238, v232
	v_mul_f32_e32 v232, 0xbfb8aa3b, v231
	v_exp_f32_e32 v239, v232
	v_pk_mul_f32 v[232:233], v[234:235], v[236:237]
	v_add_f32_e32 v234, 1.0, v238
	v_rcp_f32_e32 v234, v234
	v_add_f32_e32 v235, 1.0, v239
	v_rcp_f32_e32 v235, v235
	v_pk_fma_f32 v[218:219], v[148:149], v[218:219], v[220:221]
	v_pk_fma_f32 v[228:229], v[130:131], v[228:229], v[142:143]
	v_pk_fma_f32 v[218:219], v[188:189], v[144:145], v[218:219]
	v_pk_fma_f32 v[226:227], v[134:135], v[226:227], v[228:229]
	v_mul_f32_e32 v220, 0xbfb8aa3b, v218
	v_pk_mul_f32 v[228:229], v[230:231], v[234:235]
	v_exp_f32_e32 v230, v220
	v_mul_f32_e32 v220, 0xbfb8aa3b, v219
	v_exp_f32_e32 v231, v220
	v_pk_fma_f32 v[226:227], v[186:187], v[138:139], v[226:227]
	v_pk_fma_f32 v[216:217], v[128:129], v[216:217], v[140:141]
	v_pk_mul_f32 v[220:221], v[226:227], v[228:229]
	v_add_f32_e32 v226, 1.0, v230
	v_add_f32_e32 v227, 1.0, v231
	v_rcp_f32_e32 v226, v226
	v_rcp_f32_e32 v227, v227
	v_pk_fma_f32 v[214:215], v[132:133], v[214:215], v[216:217]
	v_pk_fma_f32 v[212:213], v[86:87], v[212:213], v[98:99]
	v_pk_fma_f32 v[214:215], v[184:185], v[136:137], v[214:215]
	v_pk_mul_f32 v[216:217], v[218:219], v[226:227]
	v_pk_fma_f32 v[218:219], v[102:103], v[224:225], v[114:115]
	v_pk_mul_f32 v[214:215], v[214:215], v[216:217]
	v_pk_fma_f32 v[218:219], v[110:111], v[222:223], v[218:219]
	v_pk_fma_f32 v[210:211], v[90:91], v[210:211], v[212:213]
	v_pk_fma_f32 v[218:219], v[182:183], v[106:107], v[218:219]
	v_pk_fma_f32 v[210:211], v[178:179], v[94:95], v[210:211]
	v_mul_f32_e32 v222, 0xbfb8aa3b, v218
	v_mul_f32_e32 v223, 0xbfb8aa3b, v219
	v_exp_f32_e32 v222, v222
	v_exp_f32_e32 v223, v223
	v_add_f32_e32 v216, 1.0, v222
	v_add_f32_e32 v217, 1.0, v223
	v_rcp_f32_e32 v216, v216
	v_rcp_f32_e32 v217, v217
	s_nop 0
	v_pk_mul_f32 v[212:213], v[218:219], v[216:217]
	s_nop 0
	v_pk_mul_f32 v[216:217], v[210:211], v[212:213]
	v_cvt_pk_bf16_f32 v210, v214, v215
	v_mov_b64_e32 v[214:215], s[20:21]
	v_mad_i64_i32 v[214:215], s[10:11], v246, s83, v[214:215]
	v_cvt_pk_bf16_f32 v211, v220, v221
	v_cvt_pk_bf16_f32 v212, v232, v233
	v_cvt_pk_bf16_f32 v213, v216, v217
	v_lshl_add_u64 v[214:215], v[208:209], 1, v[214:215]
	global_store_dwordx4 v[214:215], v[210:213], off
